# mixer A: selected-key index look-ups batched (one LDS wait per step), cross-row max via permlane16 swap instead of ds_bpermute
# speedup vs baseline: 1.1539x; 1.0039x over previous
; DI float fexp2(float x) { return __builtin_amdgcn_exp2f(x); }
; DI f32x4 mfma16(bf16x8 a, bf16x8 b, f32x4 c) { return __builtin_amdgcn_mfma_f32_16x16x32_bf16(a, b, c, 0, 0, 0); }
; DI void lds_fence() { asm volatile("s_waitcnt lgkmcnt(0)" ::: "memory"); __builtin_amdgcn_wave_barrier(); }
; DI float half_max(float v) { auto rr = __builtin_amdgcn_permlane32_swap(__float_as_uint(v), __float_as_uint(v), false, false); return fmaxf(__uint_as_float(rr[0]), __uint_as_float(rr[1])); }
; #define A_LOAD(j) do { _Pragma("unroll") for (int i = 0; i < 4; ++i) { const int row = (lane >> 3) + 8 * i, ch = lane & 7, e = 32 * (j) + row; \
;       const int tokk = (e < count) ? (int)sel_l[e] : 0; const size_t off = (size_t)tokk * NPE + ch * 8; R.k[i] = *(const u32x4*)(Kg + off); R.v[i] = *(const u32x4*)(Vg + off); } } while (0)
; DI void attn_step16(const bf16* Kt, const bf16* Vt, const bf16x8 (&qf)[2], f32x4 (&o)[4], float& m, float& l, int nvalid  , float c2, int lane) {
;     ...
;   f32x4 s0 = {0.f, 0.f, 0.f, 0.f}, s1 = {0.f, 0.f, 0.f, 0.f};
; #pragma unroll
;   for (int ks = 0; ks < 2; ++ks) {
;     const bf16x8 k0 = *(const bf16x8*)(Kt + c * WP + ks * 32 + qd * 8);
;     const bf16x8 k1 = *(const bf16x8*)(Kt + (16 + c) * WP + ks * 32 + qd * 8);
;     s0 = mfma16(k0, qf[ks], s0); s1 = mfma16(k1, qf[ks], s1);
;   }
;   float mx = -INFINITY;
; #pragma unroll
;   for (int j = 0; j < 4; ++j) { if (4 * qd + j >= nvalid) s0[j] = -INFINITY; if (16 + 4 * qd + j >= nvalid) s1[j] = -INFINITY; mx = fmaxf(mx, fmaxf(s0[j], s1[j])); }
;   mx = fmaxf(mx, __shfl_xor(mx, 16)); mx = half_max(mx);
;   const float mxs = mx * c2;
;   if (__any(mxs > m + 6.f)) {
;     const float mn = fmaxf(m, mxs); const float alpha = fexp2(m - mn); l *= alpha;
; #pragma unroll
;     for (int d = 0; d < 4; ++d) o[d] = o[d] * alpha;
;     m = mn;
;   }
; DI void mixerA_item(const Params& p, int item, bf16* Ks, bf16* Vs, int lane) {
;     ...
;   A_LOAD(0);
;   for (int j = 0; j < nsteps; ++j) {
;     lds_fence();
;     kv_store(R, Ks, Vs, lane);
;     lds_fence();
;     if (j + 1 < nsteps) A_LOAD(j + 1);
;     attn_step16(Ks, Vs, qf, o, m, l, count - 32 * j, 0.125f * LOG2E, lane);
.LBB0_2157:
	s_waitcnt lgkmcnt(0)
	s_waitcnt vmcnt(7)
	ds_write_b128 v93, v[20:23]
	s_waitcnt vmcnt(6)
	ds_write_b128 v93, v[24:27] offset:4608
	s_waitcnt vmcnt(5)
	ds_write_b128 v93, v[28:31] offset:1152
	s_waitcnt vmcnt(4)
	ds_write_b128 v93, v[32:35] offset:5760
	s_waitcnt vmcnt(3)
	ds_write_b128 v93, v[40:43] offset:2304
	s_waitcnt vmcnt(2)
	ds_write_b128 v93, v[44:47] offset:6912
	s_waitcnt vmcnt(0)
	ds_write_b128 v93, v[52:55] offset:3456
	ds_write_b128 v93, v[48:51] offset:8064
	s_waitcnt lgkmcnt(0)
	s_add_i32 s31, s31, 1
	v_cmp_lt_u32_e32 vcc, s31, v111
	s_and_saveexec_b64 s[6:7], vcc
	s_cbranch_execz .LBB0_2167
	ds_read_u16 v20, v113
	ds_read_u16 v28, v113 offset:16
	ds_read_u16 v40, v113 offset:32
	ds_read_u16 v48, v113 offset:48
	v_subrev_u32_e32 v200, 24, v112
	v_add_u32_e32 v201, -16, v112
	v_add_u32_e32 v202, -8, v112
	v_cmp_le_u32_e64 s[8:9], v200, v81
	v_cmp_le_u32_e64 s[10:11], v201, v81
	v_cmp_le_u32_e64 s[12:13], v202, v81
	v_cmp_le_u32_e64 s[14:15], v112, v81
	s_waitcnt lgkmcnt(0)
	v_mul_u32_u24_e32 v20, 0xc00, v20
	v_mul_u32_u24_e32 v28, 0xc00, v28
	v_mul_u32_u24_e32 v40, 0xc00, v40
	v_mul_u32_u24_e32 v48, 0xc00, v48
	v_cndmask_b32_e64 v20, 0, v20, s[8:9]
	v_cndmask_b32_e64 v28, 0, v28, s[10:11]
	v_cndmask_b32_e64 v40, 0, v40, s[12:13]
	v_cndmask_b32_e64 v48, 0, v48, s[14:15]
	v_or_b32_e32 v20, v20, v72
	v_or_b32_e32 v28, v28, v72
	v_or_b32_e32 v40, v40, v72
	v_or_b32_e32 v48, v48, v72
	v_lshlrev_b32_e32 v68, 1, v20
	v_lshl_add_u64 v[200:201], v[86:87], 0, v[68:69]
	v_lshlrev_b32_e32 v68, 1, v28
	v_lshl_add_u64 v[202:203], v[86:87], 0, v[68:69]
	v_lshlrev_b32_e32 v68, 1, v40
	v_lshl_add_u64 v[204:205], v[86:87], 0, v[68:69]
	v_lshlrev_b32_e32 v68, 1, v48
	v_lshl_add_u64 v[206:207], v[86:87], 0, v[68:69]
	global_load_dwordx4 v[20:23], v[200:201], off offset:1024
	global_load_dwordx4 v[24:27], v[200:201], off offset:1152
	global_load_dwordx4 v[28:31], v[202:203], off offset:1024
	global_load_dwordx4 v[32:35], v[202:203], off offset:1152
	global_load_dwordx4 v[40:43], v[204:205], off offset:1024
	global_load_dwordx4 v[44:47], v[204:205], off offset:1152
	global_load_dwordx4 v[52:55], v[206:207], off offset:1024
	global_load_dwordx4 v[48:51], v[206:207], off offset:1152
.LBB0_2167:
	s_or_b64 exec, exec, s[6:7]
	ds_read_b128 v[60:63], v94
	ds_read_b128 v[64:67], v94 offset:64
	ds_read_b128 v[116:119], v94 offset:2304
	ds_read_b128 v[120:123], v94 offset:2368
	v_mov_b32_e32 v68, s29
	v_cmp_lt_i32_e32 vcc, v74, v110
	s_waitcnt lgkmcnt(3)
	v_mfma_f32_16x16x32_bf16 v[60:63], v[60:63], v[0:3], 0
	v_mov_b32_e32 v124, s29
	v_cmp_lt_i32_e64 s[6:7], v96, v110
	v_cmp_lt_i32_e64 s[8:9], v97, v110
	s_waitcnt lgkmcnt(1)
	v_mfma_f32_16x16x32_bf16 v[116:119], v[116:119], v[0:3], 0
	v_cmp_lt_i32_e64 s[16:17], v98, v110
	v_cmp_lt_i32_e64 s[14:15], v99, v110
	v_cmp_lt_i32_e64 s[10:11], v100, v110
	v_mfma_f32_16x16x32_bf16 v[60:63], v[64:67], v[4:7], v[60:63]
	v_cmp_lt_i32_e64 s[12:13], v101, v110
	s_waitcnt lgkmcnt(0)
	v_mfma_f32_16x16x32_bf16 v[64:67], v[120:123], v[4:7], v[116:119]
	s_nop 4
	v_cndmask_b32_e32 v117, v68, v60, vcc
	v_cmp_lt_i32_e32 vcc, v95, v110
	v_cndmask_b32_e64 v120, v108, v61, s[6:7]
	v_max_f32_e32 v116, v117, v117
	v_cndmask_b32_e32 v68, v124, v64, vcc
	v_max_f32_e32 v115, v68, v68
	v_cndmask_b32_e64 v121, v108, v65, s[8:9]
	v_max_f32_e32 v115, v116, v115
	v_max_f32_e32 v116, v121, v121
	v_max_f32_e32 v118, v120, v120
	v_max_f32_e32 v116, v118, v116
	v_cndmask_b32_e64 v118, v108, v62, s[16:17]
	v_cndmask_b32_e64 v119, v108, v66, s[14:15]
	v_max3_f32 v122, v115, s29, v116
	v_max_f32_e32 v115, v119, v119
	v_max_f32_e32 v116, v118, v118
	v_max_f32_e32 v123, v116, v115
	v_cndmask_b32_e64 v115, v108, v63, s[10:11]
	v_cndmask_b32_e64 v116, v108, v67, s[12:13]
	v_max_f32_e32 v63, v116, v116
	v_max_f32_e32 v67, v115, v115
	v_max_f32_e32 v63, v67, v63
	v_max3_f32 v122, v122, v123, v63
	v_and_b32_e32 v63, 64, v183
	v_xor_b32_e32 v67, 16, v183
	v_add_u32_e32 v63, 64, v63
	v_cmp_lt_i32_e32 vcc, v67, v63
	s_nop 1
	v_cndmask_b32_e32 v67, v183, v67, vcc
	v_lshlrev_b32_e32 v67, 2, v67
	v_mov_b32_e32 v123, v122
	s_nop 1
	v_permlane16_swap_b32_e32 v122, v123
	v_max_f32_e32 v122, v122, v123
	v_mov_b32_e32 v123, v122
	s_nop 1
	v_permlane32_swap_b32_e32 v122, v123
	v_max_f32_e32 v123, v123, v123
	v_max_f32_e32 v122, v122, v122
	v_max_f32_e32 v122, v122, v123
	v_mul_f32_e32 v122, 0x3e38aa3b, v122
	v_add_f32_e32 v123, 0x40c00000, v114
	v_cmp_gt_f32_e32 vcc, v122, v123
	s_cbranch_vccz .LBB0_2156
	v_max_f32_e32 v56, v122, v122
	v_max_f32_e32 v57, v114, v114
	v_max_f32_e32 v122, v57, v56
	v_sub_f32_e32 v56, v114, v122
	v_exp_f32_e32 v58, v56
	v_mov_b32_e32 v114, v122
	v_mul_f32_e32 v109, v109, v58
	v_pk_mul_f32 v[18:19], v[18:19], v[58:59] op_sel_hi:[1,0]
	v_pk_mul_f32 v[16:17], v[16:17], v[58:59] op_sel_hi:[1,0]
	v_pk_mul_f32 v[14:15], v[14:15], v[58:59] op_sel_hi:[1,0]
	v_pk_mul_f32 v[12:13], v[12:13], v[58:59] op_sel_hi:[1,0]
	v_pk_mul_f32 v[10:11], v[10:11], v[58:59] op_sel_hi:[1,0]
	v_pk_mul_f32 v[8:9], v[8:9], v[58:59] op_sel_hi:[1,0]
	v_pk_mul_f32 v[56:57], v[36:37], v[58:59] op_sel_hi:[1,0]
	v_pk_mul_f32 v[58:59], v[38:39], v[58:59] op_sel_hi:[1,0]
	s_branch .LBB0_2156
